# gate phase: work unit is one direction of a chunk (even blocks forward, odd blocks backward cumsum) on top of the scan with priority-2 critical waves
# speedup vs baseline: 1.0031x; 1.0031x over previous
.LBB0_1128:
	s_or_b64 exec, exec, s[4:5]
	v_mov_b32_e32 v2, v148
	s_cmpk_gt_i32 s2, 0x41f
	s_barrier
	s_cbranch_scc1 .LBB0_1135
	v_ashrrev_i32_e32 v3, 31, v2
	v_lshlrev_b64 v[0:1], 2, v[2:3]
	v_lshl_add_u64 v[4:5], s[80:81], 0, v[0:1]
	v_add_co_u32_e32 v8, vcc, 0x8000, v4
	v_lshl_add_u64 v[0:1], s[82:83], 0, v[0:1]
	s_nop 0
	v_addc_co_u32_e32 v9, vcc, 0, v5, vcc
	v_add_co_u32_e32 v12, vcc, 0x1000, v4
	v_readlane_b32 s4, v255, 23
	s_nop 0
	v_addc_co_u32_e32 v13, vcc, 0, v5, vcc
	v_add_co_u32_e32 v14, vcc, 0x9000, v4
	v_readlane_b32 s5, v255, 24
	s_nop 0
	v_addc_co_u32_e32 v15, vcc, 0, v5, vcc
	v_add_co_u32_e32 v22, vcc, 0x2000, v4
	global_load_dword v6, v[4:5], off
	global_load_dword v7, v[8:9], off
	s_nop 0
	global_load_dword v8, v[8:9], off offset:2048
	s_nop 0
	global_load_dword v9, v[12:13], off
	global_load_dword v10, v[14:15], off
	global_load_dword v11, v[14:15], off offset:2048
	s_nop 0
	global_load_dword v12, v[12:13], off offset:2048
	s_nop 0
	global_load_dword v13, v[4:5], off offset:2048
	v_addc_co_u32_e32 v23, vcc, 0, v5, vcc
	v_add_co_u32_e32 v16, vcc, 0xa000, v4
	v_lshlrev_b32_e32 v40, 4, v2
	s_nop 0
	v_addc_co_u32_e32 v17, vcc, 0, v5, vcc
	v_add_co_u32_e32 v20, vcc, 0x3000, v4
	s_lshr_b32 s3, s2, 1
	s_lshl_b32 s3, s3, 6
	s_nop 0
	v_addc_co_u32_e32 v21, vcc, 0, v5, vcc
	v_add_co_u32_e32 v24, vcc, 0xb000, v4
	s_lshl_b32 s12, s50, 5
	s_nop 0
	v_addc_co_u32_e32 v25, vcc, 0, v5, vcc
	v_add_co_u32_e32 v30, vcc, 0x4000, v4
	global_load_dword v14, v[22:23], off
	global_load_dword v15, v[16:17], off
	s_nop 0
	global_load_dword v16, v[16:17], off offset:2048
	s_nop 0
	global_load_dword v17, v[20:21], off
	global_load_dword v18, v[24:25], off
	global_load_dword v19, v[24:25], off offset:2048
	s_nop 0
	global_load_dword v20, v[20:21], off offset:2048
	s_nop 0
	global_load_dword v21, v[22:23], off offset:2048
	v_addc_co_u32_e32 v31, vcc, 0, v5, vcc
	v_add_co_u32_e32 v24, vcc, 0xc000, v4
	s_mov_b32 s13, 0xbfb8aa3b
	s_nop 0
	v_addc_co_u32_e32 v25, vcc, 0, v5, vcc
	v_add_co_u32_e32 v28, vcc, 0x5000, v4
	s_mov_b32 s14, 0x800000
	s_nop 0
	v_addc_co_u32_e32 v29, vcc, 0, v5, vcc
	v_add_co_u32_e32 v32, vcc, 0xd000, v4
	s_mov_b32 s15, 0x3f317217
	s_nop 0
	v_addc_co_u32_e32 v33, vcc, 0, v5, vcc
	v_add_co_u32_e32 v38, vcc, 0x6000, v4
	global_load_dword v22, v[30:31], off
	global_load_dword v23, v[24:25], off
	s_nop 0
	global_load_dword v24, v[24:25], off offset:2048
	s_nop 0
	global_load_dword v25, v[28:29], off
	global_load_dword v26, v[32:33], off
	global_load_dword v27, v[32:33], off offset:2048
	s_nop 0
	global_load_dword v28, v[28:29], off offset:2048
	s_nop 0
	global_load_dword v29, v[30:31], off offset:2048
	v_addc_co_u32_e32 v39, vcc, 0, v5, vcc
	v_add_co_u32_e32 v32, vcc, 0xe000, v4
	s_mov_b32 s16, 0x7f800000
	s_nop 0
	v_addc_co_u32_e32 v33, vcc, 0, v5, vcc
	v_add_co_u32_e32 v36, vcc, 0x7000, v4
	v_mov_b32_e32 v41, 0x41b17218
	s_nop 0
	v_addc_co_u32_e32 v37, vcc, 0, v5, vcc
	v_add_co_u32_e32 v4, vcc, 0xf000, v4
	s_mov_b32 s17, 0x3db8aa3b
	s_nop 0
	v_addc_co_u32_e32 v5, vcc, 0, v5, vcc
	global_load_dword v30, v[38:39], off
	global_load_dword v31, v[32:33], off
	s_nop 0
	global_load_dword v32, v[32:33], off offset:2048
	s_nop 0
	global_load_dword v33, v[36:37], off
	global_load_dword v34, v[4:5], off
	global_load_dword v35, v[4:5], off offset:2048
	s_nop 0
	global_load_dword v36, v[36:37], off offset:2048
	s_nop 0
	global_load_dword v37, v[38:39], off offset:2048
	s_nop 0
	global_load_dword v38, v[0:1], off
	global_load_dword v39, v[0:1], off offset:2048
	v_lshlrev_b32_e32 v0, 2, v2
	v_ashrrev_i32_e32 v1, 31, v0
	v_lshlrev_b64 v[4:5], 1, v[2:3]
	v_lshl_add_u64 v[0:1], v[0:1], 2, s[4:5]
	v_lshl_add_u64 v[2:3], s[62:63], 0, v[4:5]
	v_lshl_add_u64 v[4:5], s[54:55], 0, v[4:5]
	s_mov_b64 s[4:5], 0x10600000
	v_lshl_add_u64 v[4:5], v[4:5], 0, s[4:5]
	s_lshr_b32 s10, s2, 1
.LBB0_1130:
	s_ashr_i32 s11, s10, 31
	s_lshl_b64 s[4:5], s[10:11], 13
	v_lshl_add_u64 v[42:43], v[0:1], 0, s[4:5]
	s_barrier
	global_load_dwordx4 v[44:47], v[42:43], off
	s_mov_b32 s11, 0
	v_mov_b32_e32 v42, 0
	s_mov_b32 s18, 0
	s_waitcnt vmcnt(0)
	ds_write_b128 v40, v[44:47]
	s_waitcnt lgkmcnt(0)
	s_barrier
	s_bitcmp1_b32 s2, 0
	s_cbranch_scc1 .Lgate_bwd
.LBB0_1131:
	v_mov_b32_e32 v43, s18
	ds_read_b128 v[44:47], v43
	ds_read_b128 v[48:51], v43 offset:16
	ds_read_b128 v[52:55], v43 offset:32
	ds_read_b128 v[56:59], v43 offset:48
	ds_read_b128 v[60:63], v43 offset:128
	ds_read_b128 v[64:67], v43 offset:144
	ds_read_b128 v[68:71], v43 offset:160
	ds_read_b128 v[72:75], v43 offset:176
	ds_read_b128 v[76:79], v43 offset:256
	ds_read_b128 v[80:83], v43 offset:272
	ds_read_b128 v[84:87], v43 offset:288
	ds_read_b128 v[88:91], v43 offset:304
	ds_read_b128 v[92:95], v43 offset:384
	ds_read_b128 v[96:99], v43 offset:400
	ds_read_b128 v[100:103], v43 offset:416
	ds_read_b128 v[104:107], v43 offset:432
	s_waitcnt lgkmcnt(14)
	v_fma_f32 v43, v44, v6, v38
	s_waitcnt lgkmcnt(11)
	v_fma_f32 v44, v60, v6, v38
	s_waitcnt lgkmcnt(7)
	v_fma_f32 v60, v76, v6, v38
	v_fmac_f32_e32 v43, v45, v13
	v_fmac_f32_e32 v44, v61, v13
	v_fmac_f32_e32 v60, v77, v13
	v_fmac_f32_e32 v43, v46, v9
	s_waitcnt lgkmcnt(3)
	v_fma_f32 v76, v92, v6, v38
	v_fmac_f32_e32 v44, v62, v9
	v_fmac_f32_e32 v60, v78, v9
	v_fmac_f32_e32 v43, v47, v12
	v_fmac_f32_e32 v76, v93, v13
	v_fmac_f32_e32 v44, v63, v12
	v_fmac_f32_e32 v60, v79, v12
	v_fmac_f32_e32 v43, v48, v14
	v_fmac_f32_e32 v76, v94, v9
	v_fmac_f32_e32 v44, v64, v14
	v_fmac_f32_e32 v60, v80, v14
	v_fmac_f32_e32 v43, v49, v21
	v_fmac_f32_e32 v76, v95, v12
	v_fmac_f32_e32 v44, v65, v21
	v_fmac_f32_e32 v60, v81, v21
	v_fmac_f32_e32 v43, v50, v17
	s_waitcnt lgkmcnt(2)
	v_fmac_f32_e32 v76, v96, v14
	v_fmac_f32_e32 v44, v66, v17
	v_fmac_f32_e32 v60, v82, v17
	v_fmac_f32_e32 v43, v51, v20
	v_fmac_f32_e32 v76, v97, v21
	v_fmac_f32_e32 v44, v67, v20
	v_fmac_f32_e32 v60, v83, v20
	v_fmac_f32_e32 v43, v52, v22
	v_fmac_f32_e32 v76, v98, v17
	v_fmac_f32_e32 v44, v68, v22
	v_fmac_f32_e32 v60, v84, v22
	v_fmac_f32_e32 v43, v53, v29
	v_fmac_f32_e32 v76, v99, v20
	v_fmac_f32_e32 v44, v69, v29
	v_fmac_f32_e32 v60, v85, v29
	v_fmac_f32_e32 v43, v54, v25
	s_waitcnt lgkmcnt(1)
	v_fmac_f32_e32 v76, v100, v22
	v_fmac_f32_e32 v44, v70, v25
	v_fmac_f32_e32 v60, v86, v25
	v_fmac_f32_e32 v43, v55, v28
	v_fmac_f32_e32 v76, v101, v29
	v_fmac_f32_e32 v44, v71, v28
	v_fmac_f32_e32 v60, v87, v28
	v_fmac_f32_e32 v43, v56, v30
	v_fmac_f32_e32 v76, v102, v25
	v_fmac_f32_e32 v44, v72, v30
	v_fmac_f32_e32 v60, v88, v30
	v_fmac_f32_e32 v43, v57, v37
	v_fmac_f32_e32 v76, v103, v28
	v_fmac_f32_e32 v44, v73, v37
	v_fmac_f32_e32 v60, v89, v37
	v_fmac_f32_e32 v43, v58, v33
	s_waitcnt lgkmcnt(0)
	v_fmac_f32_e32 v76, v104, v30
	v_fmac_f32_e32 v44, v74, v33
	v_fmac_f32_e32 v60, v90, v33
	v_fmac_f32_e32 v43, v59, v36
	v_fmac_f32_e32 v76, v105, v37
	v_fmac_f32_e32 v44, v75, v36
	v_fmac_f32_e32 v60, v91, v36
	v_min_f32_e32 v45, 0, v43
	v_mul_f32_e64 v43, |v43|, s13
	v_fmac_f32_e32 v76, v106, v33
	v_min_f32_e32 v46, 0, v44
	v_mul_f32_e64 v44, |v44|, s13
	v_mul_f32_e64 v48, |v60|, s13
	v_exp_f32_e32 v43, v43
	v_fmac_f32_e32 v76, v107, v36
	v_exp_f32_e32 v44, v44
	v_exp_f32_e32 v48, v48
	s_add_i32 s4, s3, s11
	v_mul_f32_e64 v50, |v76|, s13
	s_ashr_i32 s5, s4, 31
	s_add_i32 s6, s4, 1
	s_add_i32 s8, s4, 2
	v_exp_f32_e32 v50, v50
	s_add_i32 s20, s4, 3
	s_lshl_b64 s[4:5], s[4:5], 10
	s_ashr_i32 s7, s6, 31
	s_ashr_i32 s9, s8, 31
	v_add_f32_e32 v43, 1.0, v43
	v_lshl_add_u64 v[108:109], v[2:3], 0, s[4:5]
	s_lshl_b64 s[4:5], s[6:7], 10
	s_lshl_b64 s[6:7], s[8:9], 10
	v_add_f32_e32 v44, 1.0, v44
	v_add_f32_e32 v48, 1.0, v48
	v_cmp_gt_f32_e32 vcc, s14, v43
	s_ashr_i32 s21, s20, 31
	v_lshl_add_u64 v[110:111], v[2:3], 0, s[4:5]
	v_lshl_add_u64 v[112:113], v[2:3], 0, s[6:7]
	v_cndmask_b32_e64 v51, 0, 32, vcc
	v_cmp_gt_f32_e64 s[4:5], s14, v44
	v_cmp_gt_f32_e64 s[6:7], s14, v48
	s_lshl_b64 s[8:9], s[20:21], 10
	v_add_f32_e32 v50, 1.0, v50
	v_cndmask_b32_e64 v52, 0, 32, s[4:5]
	v_cndmask_b32_e64 v53, 0, 32, s[6:7]
	v_ldexp_f32 v43, v43, v51
	v_lshl_add_u64 v[114:115], v[2:3], 0, s[8:9]
	v_cmp_gt_f32_e64 s[8:9], s14, v50
	v_ldexp_f32 v44, v44, v52
	v_ldexp_f32 v48, v48, v53
	v_log_f32_e32 v43, v43
	v_cndmask_b32_e64 v54, 0, 32, s[8:9]
	v_log_f32_e32 v44, v44
	v_log_f32_e32 v48, v48
	v_ldexp_f32 v50, v50, v54
	v_log_f32_e32 v50, v50
	v_mul_f32_e32 v55, 0x3f317217, v43
	v_mul_f32_e32 v56, 0x3f317217, v44
	v_mul_f32_e32 v57, 0x3f317217, v48
	v_fma_f32 v55, v43, s15, -v55
	v_fma_f32 v56, v44, s15, -v56
	v_fma_f32 v57, v48, s15, -v57
	v_fmac_f32_e32 v55, 0x3377d1cf, v43
	v_cndmask_b32_e64 v54, 0, v41, s[8:9]
	v_mul_f32_e32 v58, 0x3f317217, v50
	v_fmac_f32_e32 v56, 0x3377d1cf, v44
	v_fmac_f32_e32 v57, 0x3377d1cf, v48
	v_fmac_f32_e32 v55, 0x3f317217, v43
	v_cmp_lt_f32_e64 s[8:9], |v43|, s16
	v_cndmask_b32_e32 v51, 0, v41, vcc
	v_cndmask_b32_e64 v52, 0, v41, s[4:5]
	v_fma_f32 v58, v50, s15, -v58
	v_fmac_f32_e32 v56, 0x3f317217, v44
	v_cmp_lt_f32_e64 vcc, |v44|, s16
	v_fmac_f32_e32 v57, 0x3f317217, v48
	v_cmp_lt_f32_e64 s[4:5], |v48|, s16
	v_cndmask_b32_e64 v43, v43, v55, s[8:9]
	v_cndmask_b32_e64 v53, 0, v41, s[6:7]
	v_fmac_f32_e32 v58, 0x3377d1cf, v50
	v_cndmask_b32_e32 v44, v44, v56, vcc
	v_cndmask_b32_e64 v48, v48, v57, s[4:5]
	v_sub_f32_e32 v43, v43, v51
	v_min_f32_e32 v47, 0, v60
	v_fmac_f32_e32 v58, 0x3f317217, v50
	v_cmp_lt_f32_e64 s[6:7], |v50|, s16
	v_sub_f32_e32 v44, v44, v52
	v_sub_f32_e32 v48, v48, v53
	v_sub_f32_e32 v43, v45, v43
	v_cndmask_b32_e64 v50, v50, v58, s[6:7]
	v_sub_f32_e32 v44, v46, v44
	v_sub_f32_e32 v45, v47, v48
	v_fmamk_f32 v47, v43, 0x3db8aa3b, v42
	v_fma_mixlo_f16 v42, v43, s17, v42
	v_min_f32_e32 v49, 0, v76
	v_sub_f32_e32 v50, v50, v54
	global_store_short v[108:109], v42, off
	v_fmamk_f32 v42, v44, 0x3db8aa3b, v47
	v_fma_mixlo_f16 v43, v44, s17, v47
	s_add_i32 s11, s11, 4
	s_addk_i32 s18, 0x200
	v_sub_f32_e32 v46, v49, v50
	global_store_short v[110:111], v43, off
	v_fmamk_f32 v43, v45, 0x3db8aa3b, v42
	v_fma_mixlo_f16 v42, v45, s17, v42
	s_cmp_lg_u32 s11, 64
	global_store_short v[112:113], v42, off
	v_fmamk_f32 v42, v46, 0x3db8aa3b, v43
	v_fma_mixlo_f16 v43, v46, s17, v43
	global_store_short v[114:115], v43, off
	s_cbranch_scc1 .LBB0_1131
	s_branch .Lgate_next
.Lgate_bwd:
	v_mov_b32_e32 v42, 0
	s_mov_b32 s11, 0
	s_movk_i32 s18, 0x1e40

.Lgate_next:
	s_lshr_b32 s4, s50, 1
	s_add_i32 s10, s10, s4
	s_add_i32 s3, s3, s12
	s_cmpk_gt_i32 s10, 0x41f
	s_cbranch_scc0 .LBB0_1130
